# C + all eight GEMM K-loop heads padded to byte phase 56 mod 64 (code placement scan)
# speedup vs baseline: 1.0037x; 1.0012x over previous
;     __device__ bool next(int i, Unit& u) const { if (i != 0) return false; return so.next(round, u); }
;     __device__ __forceinline__ bool next(int i, Unit& u) const { if (i > 0 || !on) return false; u.pm = pm; u.pn = 0; return true; }
; #define PG8_STAGE(bufoff, gbase, voff) do { _Pragma("unroll") for (int _i = 0; _i < 2; ++_i) \
;         __builtin_amdgcn_global_load_lds((const unsigned*)((const char*)(gbase) + (voff)[_i]), (PG8_LAS unsigned*)(lds + (bufoff) + ldsw + _i * 8192), 16, 0, 0); } while (0)
; #define PG8_LDA(dst, b, h) do { _Pragma("unroll") for (int m = 0; m < 4; ++m) _Pragma("unroll") for (int k = 0; k < 2; ++k) dst[m][k] = *(const PG8_LAS bf16x8*)(lds + PG8_SA(b, h) + aoff + m * 2048 + k * 1024); } while (0)
; #define PG8_LDB(dst, b, h) do { _Pragma("unroll") for (int n = 0; n < 2; ++n) _Pragma("unroll") for (int k = 0; k < 2; ++k) dst[n][k] = *(const PG8_LAS bf16x8*)(lds + PG8_SB(b, h) + boff + n * 2048 + k * 1024); } while (0)
; #define PG8_WAIT_V(n) asm volatile("s_waitcnt vmcnt(" #n ")" ::: "memory")
; #define PG8_WAIT_L(n) asm volatile("s_waitcnt lgkmcnt(" #n ")" ::: "memory")
; #define PG8_BAR __builtin_amdgcn_s_barrier()
; template <class Epi, class Sched, bool ALIGN_EPI = false, bool SP2 = false, bool MIDHOOK = false>
; __device__ __forceinline__ void gemm_phase(PG8_LAS unsigned char* lds, const Gemm g, const Sched& S, const Epi& E) {
;     ...
;         const bool has_next = S.next(ui + 1, nxt);
;         const char* nA = has_next ? (const char*)g.A + (size_t)nxt.pm * tstep : cA; const char* nB = has_next ? (const char*)g.Bt + (size_t)nxt.pn * tstep : cB;
;         for (int t = 0; t < nt; t += 2) {
;             if constexpr (MIDHOOK) { if (t == nt / 2) E.mid(acc, cur, wr, wc, fr, fq); }
;             const bool last = (t == nt - 2);
;             const char* a1 = cA + (size_t)(t + 1) * kstep;
;             const char* a2 = last ? nA : cA + (size_t)(t + 2) * kstep; const char* b2 = last ? nB : cB + (size_t)(t + 2) * kstep;
;             const char* a3 = a2 + kstep; const char* b3 = b2 + kstep;
;             if (last && has_next) S.a_ready(nxt);
;             if constexpr (SP2) {
;             PG8_LDB(B0, 0, 0); PG8_LDB(B1, 0, 1); PG8_SCHED; PG8_LDA(At, 0, 0); PG8_STAGE(PG8_SA(1, 1), a1 + hstep, voffA);
;             PG8_WAIT_V(8); PG8_WAIT_L(0); PG8_BAR; PG8_MMA(0, 0, At, B0); PG8_MMA(0, 1, At, B1); PG8_BAR; PG8_SCHED;
.LBB0_190:
	s_ashr_i32 s41, s40, 31
	s_lshl_b64 s[42:43], s[40:41], 19
	v_readlane_b32 s12, v243, 48
	v_readlane_b32 s13, v243, 49
	s_add_u32 s42, s12, s42
	s_addc_u32 s43, s13, s43
	s_and_b64 s[44:45], s[0:1], exec
	s_cselect_b32 s5, s43, s7
	s_cselect_b32 s41, s42, s6
	s_ashr_i32 s39, s38, 31
	s_lshl_b64 s[44:45], s[38:39], 19
	s_add_u32 s44, s24, s44
	s_addc_u32 s45, s25, s45
	s_and_b64 s[48:49], s[0:1], exec
	s_cselect_b32 s39, s45, s9
	s_cselect_b32 s62, s44, s8
	s_add_u32 s6, s6, 0x40080
	s_addc_u32 s7, s7, 0
	s_add_u32 s63, s8, 0x100
	v_mov_b32_e32 v0, 0
	s_addc_u32 s64, s9, 0
	s_mov_b32 s65, -2
	v_mov_b32_e32 v1, v0
	v_mov_b32_e32 v2, v0
	v_mov_b32_e32 v3, v0
	v_mov_b32_e32 v8, v0
	v_mov_b32_e32 v9, v0
	v_mov_b32_e32 v10, v0
	v_mov_b32_e32 v11, v0
	v_mov_b32_e32 v16, v0
	v_mov_b32_e32 v17, v0
	v_mov_b32_e32 v18, v0
	v_mov_b32_e32 v19, v0
	v_mov_b32_e32 v24, v0
	v_mov_b32_e32 v25, v0
	v_mov_b32_e32 v26, v0
	v_mov_b32_e32 v27, v0
	v_mov_b32_e32 v32, v0
	v_mov_b32_e32 v33, v0
	v_mov_b32_e32 v34, v0
	v_mov_b32_e32 v35, v0
	v_mov_b32_e32 v40, v0
	v_mov_b32_e32 v41, v0
	v_mov_b32_e32 v42, v0
	v_mov_b32_e32 v43, v0
	v_mov_b32_e32 v48, v0
	v_mov_b32_e32 v49, v0
	v_mov_b32_e32 v50, v0
	v_mov_b32_e32 v51, v0
	v_mov_b32_e32 v56, v0
	v_mov_b32_e32 v57, v0
	v_mov_b32_e32 v58, v0
	v_mov_b32_e32 v59, v0
	v_mov_b32_e32 v4, v0
	v_mov_b32_e32 v5, v0
	v_mov_b32_e32 v6, v0
	v_mov_b32_e32 v7, v0
	v_mov_b32_e32 v12, v0
	v_mov_b32_e32 v13, v0
	v_mov_b32_e32 v14, v0
	v_mov_b32_e32 v15, v0
	v_mov_b32_e32 v20, v0
	v_mov_b32_e32 v21, v0
	v_mov_b32_e32 v22, v0
	v_mov_b32_e32 v23, v0
	v_mov_b32_e32 v28, v0
	v_mov_b32_e32 v29, v0
	v_mov_b32_e32 v30, v0
	v_mov_b32_e32 v31, v0
	v_mov_b32_e32 v36, v0
	v_mov_b32_e32 v37, v0
	v_mov_b32_e32 v38, v0
	v_mov_b32_e32 v39, v0
	v_mov_b32_e32 v44, v0
	v_mov_b32_e32 v45, v0
	v_mov_b32_e32 v46, v0
	v_mov_b32_e32 v47, v0
	v_mov_b32_e32 v52, v0
	v_mov_b32_e32 v53, v0
	v_mov_b32_e32 v54, v0
	v_mov_b32_e32 v55, v0
	v_mov_b32_e32 v60, v0
	v_mov_b32_e32 v61, v0
	v_mov_b32_e32 v62, v0
	v_mov_b32_e32 v63, v0
	v_mov_b32_e32 v64, v0
	v_mov_b32_e32 v65, v0
	v_mov_b32_e32 v66, v0
	v_mov_b32_e32 v67, v0
	v_mov_b32_e32 v72, v0
	v_mov_b32_e32 v73, v0
	v_mov_b32_e32 v74, v0
	v_mov_b32_e32 v75, v0
	v_mov_b32_e32 v80, v0
	v_mov_b32_e32 v81, v0
	v_mov_b32_e32 v82, v0
	v_mov_b32_e32 v83, v0
	v_mov_b32_e32 v88, v0
	v_mov_b32_e32 v89, v0
	v_mov_b32_e32 v90, v0
	v_mov_b32_e32 v91, v0
	v_mov_b32_e32 v96, v0
	v_mov_b32_e32 v97, v0
	v_mov_b32_e32 v98, v0
	v_mov_b32_e32 v99, v0
	v_mov_b32_e32 v104, v0
	v_mov_b32_e32 v105, v0
	v_mov_b32_e32 v106, v0
	v_mov_b32_e32 v107, v0
	v_mov_b32_e32 v112, v0
	v_mov_b32_e32 v113, v0
	v_mov_b32_e32 v114, v0
	v_mov_b32_e32 v115, v0
	v_mov_b32_e32 v120, v0
	v_mov_b32_e32 v121, v0
	v_mov_b32_e32 v122, v0
	v_mov_b32_e32 v123, v0
	v_mov_b32_e32 v68, v0
	v_mov_b32_e32 v69, v0
	v_mov_b32_e32 v70, v0
	v_mov_b32_e32 v71, v0
	v_mov_b32_e32 v76, v0
	v_mov_b32_e32 v77, v0
	v_mov_b32_e32 v78, v0
	v_mov_b32_e32 v79, v0
	v_mov_b32_e32 v84, v0
	v_mov_b32_e32 v85, v0
	v_mov_b32_e32 v86, v0
	v_mov_b32_e32 v87, v0
	v_mov_b32_e32 v92, v0
	v_mov_b32_e32 v93, v0
	v_mov_b32_e32 v94, v0
	v_mov_b32_e32 v95, v0
	v_mov_b32_e32 v100, v0
	v_mov_b32_e32 v101, v0
	v_mov_b32_e32 v102, v0
	v_mov_b32_e32 v103, v0
	v_mov_b32_e32 v108, v0
	v_mov_b32_e32 v109, v0
	v_mov_b32_e32 v110, v0
	v_mov_b32_e32 v111, v0
	v_mov_b32_e32 v116, v0
	v_mov_b32_e32 v117, v0
	v_mov_b32_e32 v118, v0
	v_mov_b32_e32 v119, v0
	v_mov_b32_e32 v124, v0
	v_mov_b32_e32 v125, v0
	v_mov_b32_e32 v126, v0
	v_mov_b32_e32 v127, v0
	s_nop 0
	s_nop 0
	s_nop 0
	s_nop 0
.LBB0_191:
	ds_read_b128 v[128:131], v180
	s_waitcnt vmcnt(0)
	ds_read_b128 v[132:135], v180 offset:1024
	ds_read_b128 v[136:139], v180 offset:2048
	ds_read_b128 v[168:171], v180 offset:3072
	ds_read_b128 v[172:175], v181
	ds_read_b128 v[184:187], v181 offset:1024
	ds_read_b128 v[188:191], v181 offset:2048
	ds_read_b128 v[192:195], v181 offset:3072
	s_add_u32 s8, s6, 0xfffc0080
	s_addc_u32 s9, s7, -1
	s_cmp_eq_u32 s65, 12
	s_cselect_b32 s49, s5, s9
	s_cselect_b32 s48, s41, s8
	s_cselect_b32 s9, s39, s64
	s_cselect_b32 s8, s62, s63
	v_lshl_add_u64 v[230:231], s[6:7], 0, v[156:157]
	s_add_i32 m0, s47, 0xc000
	ds_read_b128 v[196:199], v182
	ds_read_b128 v[200:203], v182 offset:1024
	ds_read_b128 v[204:207], v182 offset:2048
	ds_read_b128 v[208:211], v182 offset:3072
	ds_read_b128 v[212:215], v182 offset:4096
	ds_read_b128 v[216:219], v182 offset:5120
	ds_read_b128 v[222:225], v182 offset:6144
	ds_read_b128 v[226:229], v182 offset:7168
	global_load_lds_dwordx4 v[230:231], off
	v_lshl_add_u64 v[230:231], s[6:7], 0, v[158:159]
	s_add_i32 m0, s47, 0xe000
	s_nop 0
	global_load_lds_dwordx4 v[230:231], off
	s_waitcnt vmcnt(8)
	s_waitcnt lgkmcnt(0)
	s_barrier
; #define PG8_STAGE(bufoff, gbase, voff) do { _Pragma("unroll") for (int _i = 0; _i < 2; ++_i) \
;         __builtin_amdgcn_global_load_lds((const unsigned*)((const char*)(gbase) + (voff)[_i]), (PG8_LAS unsigned*)(lds + (bufoff) + ldsw + _i * 8192), 16, 0, 0); } while (0)
; #define PG8_LDA(dst, b, h) do { _Pragma("unroll") for (int m = 0; m < 4; ++m) _Pragma("unroll") for (int k = 0; k < 2; ++k) dst[m][k] = *(const PG8_LAS bf16x8*)(lds + PG8_SA(b, h) + aoff + m * 2048 + k * 1024); } while (0)
; #define PG8_MMA(ai, bj, At, Bt) do { __builtin_amdgcn_s_setprio(1); _Pragma("unroll") for (int m = 0; m < 4; ++m) _Pragma("unroll") for (int n = 0; n < 2; ++n) _Pragma("unroll") for (int k = 0; k < 2; ++k) \
;         acc[ai][bj][m][n] = __builtin_amdgcn_mfma_f32_16x16x32_bf16(Bt[n][k], At[m][k], acc[ai][bj][m][n], 0, 0, 0); __builtin_amdgcn_s_setprio(0); } while (0)
; #define PG8_WAIT_V(n) asm volatile("s_waitcnt vmcnt(" #n ")" ::: "memory")
; #define PG8_WAIT_L(n) asm volatile("s_waitcnt lgkmcnt(" #n ")" ::: "memory")
; #define PG8_BAR __builtin_amdgcn_s_barrier()
; #define PG8_SCHED __builtin_amdgcn_sched_barrier(0)
; template <class Epi, class Sched, bool ALIGN_EPI = false, bool SP2 = false, bool MIDHOOK = false>
; __device__ __forceinline__ void gemm_phase(PG8_LAS unsigned char* lds, const Gemm g, const Sched& S, const Epi& E) {
;     ...
;             PG8_WAIT_V(8); PG8_WAIT_L(0); PG8_BAR; PG8_MMA(0, 0, At, B0); PG8_MMA(0, 1, At, B1); PG8_BAR; PG8_SCHED;
;             PG8_LDA(At, 0, 1); PG8_STAGE(PG8_SB(0, 0), b2, voffB); PG8_STAGE(PG8_SB(0, 1), b2 + hstep, voffB); PG8_STAGE(PG8_SA(0, 0), a2, voffA);
;             PG8_WAIT_V(8); PG8_WAIT_L(0); PG8_BAR; PG8_MMA(1, 0, At, B0); PG8_MMA(1, 1, At, B1); PG8_BAR; PG8_SCHED;
	s_setprio 1
	s_waitcnt lgkmcnt(0)
	v_mfma_f32_16x16x32_bf16 v[124:127], v[128:131], v[196:199], v[124:127]
	v_mfma_f32_16x16x32_bf16 v[116:119], v[136:139], v[196:199], v[116:119]
	v_mfma_f32_16x16x32_bf16 v[108:111], v[128:131], v[204:207], v[108:111]
	v_mfma_f32_16x16x32_bf16 v[100:103], v[136:139], v[204:207], v[100:103]
	v_mfma_f32_16x16x32_bf16 v[92:95], v[128:131], v[212:215], v[92:95]
	v_mfma_f32_16x16x32_bf16 v[84:87], v[136:139], v[212:215], v[84:87]
	v_mfma_f32_16x16x32_bf16 v[76:79], v[128:131], v[222:225], v[76:79]
	v_mfma_f32_16x16x32_bf16 v[68:71], v[136:139], v[222:225], v[68:71]
	v_mfma_f32_16x16x32_bf16 v[124:127], v[132:135], v[200:203], v[124:127]
	v_mfma_f32_16x16x32_bf16 v[116:119], v[168:171], v[200:203], v[116:119]
	v_mfma_f32_16x16x32_bf16 v[108:111], v[132:135], v[208:211], v[108:111]
	v_mfma_f32_16x16x32_bf16 v[100:103], v[168:171], v[208:211], v[100:103]
	v_mfma_f32_16x16x32_bf16 v[92:95], v[132:135], v[216:219], v[92:95]
	v_mfma_f32_16x16x32_bf16 v[84:87], v[168:171], v[216:219], v[84:87]
	v_mfma_f32_16x16x32_bf16 v[76:79], v[132:135], v[226:229], v[76:79]
	v_mfma_f32_16x16x32_bf16 v[68:71], v[168:171], v[226:229], v[68:71]
	s_setprio 0
	s_setprio 1
	v_mfma_f32_16x16x32_bf16 v[120:123], v[172:175], v[196:199], v[120:123]
	v_mfma_f32_16x16x32_bf16 v[112:115], v[188:191], v[196:199], v[112:115]
	v_mfma_f32_16x16x32_bf16 v[104:107], v[172:175], v[204:207], v[104:107]
	v_mfma_f32_16x16x32_bf16 v[96:99], v[188:191], v[204:207], v[96:99]
	v_mfma_f32_16x16x32_bf16 v[88:91], v[172:175], v[212:215], v[88:91]
	v_mfma_f32_16x16x32_bf16 v[80:83], v[188:191], v[212:215], v[80:83]
	v_mfma_f32_16x16x32_bf16 v[72:75], v[172:175], v[222:225], v[72:75]
	v_mfma_f32_16x16x32_bf16 v[64:67], v[188:191], v[222:225], v[64:67]
	v_mfma_f32_16x16x32_bf16 v[120:123], v[184:187], v[200:203], v[120:123]
	v_mfma_f32_16x16x32_bf16 v[112:115], v[192:195], v[200:203], v[112:115]
	v_mfma_f32_16x16x32_bf16 v[104:107], v[184:187], v[208:211], v[104:107]
	v_mfma_f32_16x16x32_bf16 v[96:99], v[192:195], v[208:211], v[96:99]
	v_mfma_f32_16x16x32_bf16 v[88:91], v[184:187], v[216:219], v[88:91]
	v_mfma_f32_16x16x32_bf16 v[80:83], v[192:195], v[216:219], v[80:83]
	v_mfma_f32_16x16x32_bf16 v[72:75], v[184:187], v[226:229], v[72:75]
	v_mfma_f32_16x16x32_bf16 v[64:67], v[192:195], v[226:229], v[64:67]
	s_setprio 0
	s_barrier
	s_add_i32 s66, s58, s3
	v_lshl_add_u64 v[230:231], s[8:9], 0, v[142:143]
	s_mov_b32 m0, s66
	ds_read_b128 v[196:199], v182 offset:16384
	ds_read_b128 v[200:203], v182 offset:17408
	ds_read_b128 v[204:207], v182 offset:18432
	ds_read_b128 v[208:211], v182 offset:19456
	ds_read_b128 v[212:215], v182 offset:20480
	ds_read_b128 v[216:219], v182 offset:21504
	ds_read_b128 v[222:225], v182 offset:22528
	ds_read_b128 v[226:229], v182 offset:23552
	global_load_lds_dwordx4 v[230:231], off
	s_add_i32 m0, s66, 0x2000
	s_add_u32 s66, s8, 0x40000
	v_lshl_add_u64 v[232:233], s[8:9], 0, v[146:147]
	s_addc_u32 s67, s9, 0
	s_add_i32 s68, s59, s3
	global_load_lds_dwordx4 v[232:233], off
	v_lshl_add_u64 v[234:235], s[66:67], 0, v[142:143]
	s_mov_b32 m0, s68
	v_lshl_add_u64 v[236:237], s[48:49], 0, v[144:145]
	global_load_lds_dwordx4 v[234:235], off
	v_lshl_add_u64 v[234:235], s[66:67], 0, v[146:147]
	s_add_i32 m0, s68, 0x2000
	s_nop 0
	global_load_lds_dwordx4 v[234:235], off
	v_lshl_add_u64 v[234:235], s[48:49], 0, v[140:141]
	s_mov_b32 m0, s47
	s_nop 0
	global_load_lds_dwordx4 v[234:235], off
	s_mov_b32 m0, s50
	s_nop 0
	global_load_lds_dwordx4 v[236:237], off
	s_waitcnt vmcnt(8)
	s_waitcnt lgkmcnt(0)
	s_barrier
	s_setprio 1
	s_waitcnt lgkmcnt(0)
	v_mfma_f32_16x16x32_bf16 v[60:63], v[128:131], v[196:199], v[60:63]
	v_mfma_f32_16x16x32_bf16 v[52:55], v[136:139], v[196:199], v[52:55]
	v_mfma_f32_16x16x32_bf16 v[44:47], v[128:131], v[204:207], v[44:47]
	v_mfma_f32_16x16x32_bf16 v[36:39], v[136:139], v[204:207], v[36:39]
	v_mfma_f32_16x16x32_bf16 v[28:31], v[128:131], v[212:215], v[28:31]
	v_mfma_f32_16x16x32_bf16 v[20:23], v[136:139], v[212:215], v[20:23]
	v_mfma_f32_16x16x32_bf16 v[12:15], v[128:131], v[222:225], v[12:15]
	v_mfma_f32_16x16x32_bf16 v[4:7], v[136:139], v[222:225], v[4:7]
	v_mfma_f32_16x16x32_bf16 v[60:63], v[132:135], v[200:203], v[60:63]
	v_mfma_f32_16x16x32_bf16 v[52:55], v[168:171], v[200:203], v[52:55]
	v_mfma_f32_16x16x32_bf16 v[44:47], v[132:135], v[208:211], v[44:47]
	v_mfma_f32_16x16x32_bf16 v[36:39], v[168:171], v[208:211], v[36:39]
	v_mfma_f32_16x16x32_bf16 v[28:31], v[132:135], v[216:219], v[28:31]
	v_mfma_f32_16x16x32_bf16 v[20:23], v[168:171], v[216:219], v[20:23]
	v_mfma_f32_16x16x32_bf16 v[12:15], v[132:135], v[226:229], v[12:15]
	v_mfma_f32_16x16x32_bf16 v[4:7], v[168:171], v[226:229], v[4:7]
	s_setprio 0
	s_setprio 1
	v_mfma_f32_16x16x32_bf16 v[56:59], v[172:175], v[196:199], v[56:59]
	v_mfma_f32_16x16x32_bf16 v[48:51], v[188:191], v[196:199], v[48:51]
	v_mfma_f32_16x16x32_bf16 v[40:43], v[172:175], v[204:207], v[40:43]
	v_mfma_f32_16x16x32_bf16 v[32:35], v[188:191], v[204:207], v[32:35]
	v_mfma_f32_16x16x32_bf16 v[24:27], v[172:175], v[212:215], v[24:27]
	v_mfma_f32_16x16x32_bf16 v[16:19], v[188:191], v[212:215], v[16:19]
	v_mfma_f32_16x16x32_bf16 v[8:11], v[172:175], v[222:225], v[8:11]
	v_mfma_f32_16x16x32_bf16 v[0:3], v[188:191], v[222:225], v[0:3]
	v_mfma_f32_16x16x32_bf16 v[56:59], v[184:187], v[200:203], v[56:59]
	v_mfma_f32_16x16x32_bf16 v[48:51], v[192:195], v[200:203], v[48:51]
	v_mfma_f32_16x16x32_bf16 v[40:43], v[184:187], v[208:211], v[40:43]
	v_mfma_f32_16x16x32_bf16 v[32:35], v[192:195], v[208:211], v[32:35]
	v_mfma_f32_16x16x32_bf16 v[24:27], v[184:187], v[216:219], v[24:27]
	v_mfma_f32_16x16x32_bf16 v[16:19], v[192:195], v[216:219], v[16:19]
	v_mfma_f32_16x16x32_bf16 v[8:11], v[184:187], v[226:229], v[8:11]
	v_mfma_f32_16x16x32_bf16 v[0:3], v[192:195], v[226:229], v[0:3]
	s_setprio 0
	s_barrier
; #define PG8_STAGE(bufoff, gbase, voff) do { _Pragma("unroll") for (int _i = 0; _i < 2; ++_i) \
;         __builtin_amdgcn_global_load_lds((const unsigned*)((const char*)(gbase) + (voff)[_i]), (PG8_LAS unsigned*)(lds + (bufoff) + ldsw + _i * 8192), 16, 0, 0); } while (0)
; #define PG8_LDA(dst, b, h) do { _Pragma("unroll") for (int m = 0; m < 4; ++m) _Pragma("unroll") for (int k = 0; k < 2; ++k) dst[m][k] = *(const PG8_LAS bf16x8*)(lds + PG8_SA(b, h) + aoff + m * 2048 + k * 1024); } while (0)
; #define PG8_LDB(dst, b, h) do { _Pragma("unroll") for (int n = 0; n < 2; ++n) _Pragma("unroll") for (int k = 0; k < 2; ++k) dst[n][k] = *(const PG8_LAS bf16x8*)(lds + PG8_SB(b, h) + boff + n * 2048 + k * 1024); } while (0)
; #define PG8_MMA(ai, bj, At, Bt) do { __builtin_amdgcn_s_setprio(1); _Pragma("unroll") for (int m = 0; m < 4; ++m) _Pragma("unroll") for (int n = 0; n < 2; ++n) _Pragma("unroll") for (int k = 0; k < 2; ++k) \
;         acc[ai][bj][m][n] = __builtin_amdgcn_mfma_f32_16x16x32_bf16(Bt[n][k], At[m][k], acc[ai][bj][m][n], 0, 0, 0); __builtin_amdgcn_s_setprio(0); } while (0)
; #define PG8_WAIT_V(n) asm volatile("s_waitcnt vmcnt(" #n ")" ::: "memory")
; #define PG8_WAIT_L(n) asm volatile("s_waitcnt lgkmcnt(" #n ")" ::: "memory")
; #define PG8_BAR __builtin_amdgcn_s_barrier()
; #define PG8_SCHED __builtin_amdgcn_sched_barrier(0)
; template <class Epi, class Sched, bool ALIGN_EPI = false, bool SP2 = false, bool MIDHOOK = false>
; __device__ __forceinline__ void gemm_phase(PG8_LAS unsigned char* lds, const Gemm g, const Sched& S, const Epi& E) {
;     ...
;             PG8_LDB(B0, 1, 0); PG8_LDB(B1, 1, 1); PG8_SCHED; PG8_LDA(At, 1, 0); PG8_STAGE(PG8_SA(0, 1), a2 + hstep, voffA);
;             PG8_WAIT_V(8); PG8_WAIT_L(0); PG8_BAR; PG8_MMA(0, 0, At, B0); PG8_MMA(0, 1, At, B1); PG8_BAR; PG8_SCHED;
	s_add_i32 s66, 0, 0x18000
	v_add_u32_e32 v148, s66, v177
	s_add_i32 s67, 0, 0x1c000
	ds_read_b128 v[128:131], v148
	ds_read_b128 v[132:135], v148 offset:1024
	ds_read_b128 v[136:139], v148 offset:2048
	ds_read_b128 v[168:171], v148 offset:3072
	v_add_u32_e32 v148, s67, v177
	ds_read_b128 v[172:175], v148
	ds_read_b128 v[184:187], v148 offset:1024
	ds_read_b128 v[188:191], v148 offset:2048
	ds_read_b128 v[192:195], v148 offset:3072
	s_add_u32 s48, s48, 0x40000
	s_addc_u32 s49, s49, 0
	s_mov_b32 m0, s51
	v_lshl_add_u64 v[238:239], s[48:49], 0, v[140:141]
	ds_read_b128 v[196:199], v182 offset:32768
	ds_read_b128 v[200:203], v182 offset:33792
	ds_read_b128 v[204:207], v182 offset:34816
	ds_read_b128 v[208:211], v182 offset:35840
	ds_read_b128 v[212:215], v182 offset:36864
	ds_read_b128 v[216:219], v182 offset:37888
	ds_read_b128 v[222:225], v182 offset:38912
	ds_read_b128 v[226:229], v182 offset:39936
	global_load_lds_dwordx4 v[238:239], off
	v_lshl_add_u64 v[238:239], s[48:49], 0, v[144:145]
	s_mov_b32 m0, s52
	s_nop 0
	global_load_lds_dwordx4 v[238:239], off
	s_waitcnt vmcnt(8)
	s_waitcnt lgkmcnt(0)
	s_barrier
	s_setprio 1
	s_waitcnt lgkmcnt(0)
	v_mfma_f32_16x16x32_bf16 v[124:127], v[128:131], v[196:199], v[124:127]
	v_mfma_f32_16x16x32_bf16 v[116:119], v[136:139], v[196:199], v[116:119]
	v_mfma_f32_16x16x32_bf16 v[108:111], v[128:131], v[204:207], v[108:111]
	v_mfma_f32_16x16x32_bf16 v[100:103], v[136:139], v[204:207], v[100:103]
	v_mfma_f32_16x16x32_bf16 v[92:95], v[128:131], v[212:215], v[92:95]
	v_mfma_f32_16x16x32_bf16 v[84:87], v[136:139], v[212:215], v[84:87]
	v_mfma_f32_16x16x32_bf16 v[76:79], v[128:131], v[222:225], v[76:79]
	v_mfma_f32_16x16x32_bf16 v[68:71], v[136:139], v[222:225], v[68:71]
	v_mfma_f32_16x16x32_bf16 v[124:127], v[132:135], v[200:203], v[124:127]
	v_mfma_f32_16x16x32_bf16 v[116:119], v[168:171], v[200:203], v[116:119]
	v_mfma_f32_16x16x32_bf16 v[108:111], v[132:135], v[208:211], v[108:111]
	v_mfma_f32_16x16x32_bf16 v[100:103], v[168:171], v[208:211], v[100:103]
	v_mfma_f32_16x16x32_bf16 v[92:95], v[132:135], v[216:219], v[92:95]
	v_mfma_f32_16x16x32_bf16 v[84:87], v[168:171], v[216:219], v[84:87]
	v_mfma_f32_16x16x32_bf16 v[76:79], v[132:135], v[226:229], v[76:79]
	v_mfma_f32_16x16x32_bf16 v[68:71], v[168:171], v[226:229], v[68:71]
	s_setprio 0
	s_setprio 1
	v_mfma_f32_16x16x32_bf16 v[120:123], v[172:175], v[196:199], v[120:123]
	v_mfma_f32_16x16x32_bf16 v[112:115], v[188:191], v[196:199], v[112:115]
	v_mfma_f32_16x16x32_bf16 v[104:107], v[172:175], v[204:207], v[104:107]
	v_mfma_f32_16x16x32_bf16 v[96:99], v[188:191], v[204:207], v[96:99]
	v_mfma_f32_16x16x32_bf16 v[88:91], v[172:175], v[212:215], v[88:91]
	v_mfma_f32_16x16x32_bf16 v[80:83], v[188:191], v[212:215], v[80:83]
	v_mfma_f32_16x16x32_bf16 v[72:75], v[172:175], v[222:225], v[72:75]
	v_mfma_f32_16x16x32_bf16 v[64:67], v[188:191], v[222:225], v[64:67]
	v_mfma_f32_16x16x32_bf16 v[120:123], v[184:187], v[200:203], v[120:123]
	v_mfma_f32_16x16x32_bf16 v[112:115], v[192:195], v[200:203], v[112:115]
	v_mfma_f32_16x16x32_bf16 v[104:107], v[184:187], v[208:211], v[104:107]
	v_mfma_f32_16x16x32_bf16 v[96:99], v[192:195], v[208:211], v[96:99]
	v_mfma_f32_16x16x32_bf16 v[88:91], v[184:187], v[216:219], v[88:91]
	v_mfma_f32_16x16x32_bf16 v[80:83], v[192:195], v[216:219], v[80:83]
	v_mfma_f32_16x16x32_bf16 v[72:75], v[184:187], v[226:229], v[72:75]
	v_mfma_f32_16x16x32_bf16 v[64:67], v[192:195], v[226:229], v[64:67]
	s_setprio 0
	s_barrier
; #define PG8_STAGE(bufoff, gbase, voff) do { _Pragma("unroll") for (int _i = 0; _i < 2; ++_i) \
;         __builtin_amdgcn_global_load_lds((const unsigned*)((const char*)(gbase) + (voff)[_i]), (PG8_LAS unsigned*)(lds + (bufoff) + ldsw + _i * 8192), 16, 0, 0); } while (0)
; #define PG8_LDA(dst, b, h) do { _Pragma("unroll") for (int m = 0; m < 4; ++m) _Pragma("unroll") for (int k = 0; k < 2; ++k) dst[m][k] = *(const PG8_LAS bf16x8*)(lds + PG8_SA(b, h) + aoff + m * 2048 + k * 1024); } while (0)
; #define PG8_MMA(ai, bj, At, Bt) do { __builtin_amdgcn_s_setprio(1); _Pragma("unroll") for (int m = 0; m < 4; ++m) _Pragma("unroll") for (int n = 0; n < 2; ++n) _Pragma("unroll") for (int k = 0; k < 2; ++k) \
;         acc[ai][bj][m][n] = __builtin_amdgcn_mfma_f32_16x16x32_bf16(Bt[n][k], At[m][k], acc[ai][bj][m][n], 0, 0, 0); __builtin_amdgcn_s_setprio(0); } while (0)
; #define PG8_WAIT_V(n) asm volatile("s_waitcnt vmcnt(" #n ")" ::: "memory")
; #define PG8_WAIT_L(n) asm volatile("s_waitcnt lgkmcnt(" #n ")" ::: "memory")
; #define PG8_BAR __builtin_amdgcn_s_barrier()
; #define PG8_SCHED __builtin_amdgcn_sched_barrier(0)
; template <class Epi, class Sched, bool ALIGN_EPI = false, bool SP2 = false, bool MIDHOOK = false>
; __device__ __forceinline__ void gemm_phase(PG8_LAS unsigned char* lds, const Gemm g, const Sched& S, const Epi& E) {
;     ...
;             PG8_LDA(At, 1, 1); PG8_STAGE(PG8_SB(1, 0), b3, voffB); PG8_STAGE(PG8_SB(1, 1), b3 + hstep, voffB); PG8_STAGE(PG8_SA(1, 0), a3, voffA);
;             PG8_WAIT_V(8); PG8_WAIT_L(0); PG8_BAR; PG8_MMA(1, 0, At, B0); PG8_MMA(1, 1, At, B1); PG8_BAR; PG8_SCHED;
;     ...
;         if constexpr (ALIGN_EPI) { if (wr == 0) PG8_BAR; }
	s_add_i32 s48, s66, s3
	v_lshl_add_u64 v[230:231], v[230:231], 0, s[34:35]
	s_mov_b32 m0, s48
	ds_read_b128 v[196:199], v182 offset:49152
	ds_read_b128 v[200:203], v182 offset:50176
	ds_read_b128 v[204:207], v182 offset:51200
	ds_read_b128 v[208:211], v182 offset:52224
	ds_read_b128 v[212:215], v182 offset:53248
	ds_read_b128 v[216:219], v182 offset:54272
	ds_read_b128 v[222:225], v182 offset:55296
	ds_read_b128 v[226:229], v182 offset:56320
	global_load_lds_dwordx4 v[230:231], off
	s_add_i32 m0, s48, 0x2000
	s_add_u32 s8, s8, 0x40080
	v_lshl_add_u64 v[230:231], v[232:233], 0, s[34:35]
	s_addc_u32 s9, s9, 0
	s_add_i32 s48, s67, s3
	global_load_lds_dwordx4 v[230:231], off
	v_lshl_add_u64 v[230:231], s[8:9], 0, v[142:143]
	s_mov_b32 m0, s48
	s_nop 0
	global_load_lds_dwordx4 v[230:231], off
	v_lshl_add_u64 v[230:231], s[8:9], 0, v[146:147]
	s_add_i32 m0, s48, 0x2000
	s_nop 0
	global_load_lds_dwordx4 v[230:231], off
	v_lshl_add_u64 v[230:231], v[234:235], 0, s[34:35]
	s_mov_b32 m0, s54
	s_nop 0
	global_load_lds_dwordx4 v[230:231], off
	v_lshl_add_u64 v[230:231], v[236:237], 0, s[34:35]
	s_mov_b32 m0, s55
	s_nop 0
	global_load_lds_dwordx4 v[230:231], off
	s_waitcnt vmcnt(8)
	s_waitcnt lgkmcnt(0)
	s_barrier
	s_setprio 1
	s_waitcnt lgkmcnt(0)
	v_mfma_f32_16x16x32_bf16 v[60:63], v[128:131], v[196:199], v[60:63]
	v_mfma_f32_16x16x32_bf16 v[52:55], v[136:139], v[196:199], v[52:55]
	v_mfma_f32_16x16x32_bf16 v[44:47], v[128:131], v[204:207], v[44:47]
	v_mfma_f32_16x16x32_bf16 v[36:39], v[136:139], v[204:207], v[36:39]
	v_mfma_f32_16x16x32_bf16 v[28:31], v[128:131], v[212:215], v[28:31]
	v_mfma_f32_16x16x32_bf16 v[20:23], v[136:139], v[212:215], v[20:23]
	v_mfma_f32_16x16x32_bf16 v[12:15], v[128:131], v[222:225], v[12:15]
	v_mfma_f32_16x16x32_bf16 v[4:7], v[136:139], v[222:225], v[4:7]
	v_mfma_f32_16x16x32_bf16 v[60:63], v[132:135], v[200:203], v[60:63]
	v_mfma_f32_16x16x32_bf16 v[52:55], v[168:171], v[200:203], v[52:55]
	v_mfma_f32_16x16x32_bf16 v[44:47], v[132:135], v[208:211], v[44:47]
	v_mfma_f32_16x16x32_bf16 v[36:39], v[168:171], v[208:211], v[36:39]
	v_mfma_f32_16x16x32_bf16 v[28:31], v[132:135], v[216:219], v[28:31]
	v_mfma_f32_16x16x32_bf16 v[20:23], v[168:171], v[216:219], v[20:23]
	v_mfma_f32_16x16x32_bf16 v[12:15], v[132:135], v[226:229], v[12:15]
	v_mfma_f32_16x16x32_bf16 v[4:7], v[168:171], v[226:229], v[4:7]
	s_setprio 0
	s_setprio 1
	v_mfma_f32_16x16x32_bf16 v[56:59], v[172:175], v[196:199], v[56:59]
	v_mfma_f32_16x16x32_bf16 v[48:51], v[188:191], v[196:199], v[48:51]
	v_mfma_f32_16x16x32_bf16 v[40:43], v[172:175], v[204:207], v[40:43]
	v_mfma_f32_16x16x32_bf16 v[32:35], v[188:191], v[204:207], v[32:35]
	v_mfma_f32_16x16x32_bf16 v[24:27], v[172:175], v[212:215], v[24:27]
	v_mfma_f32_16x16x32_bf16 v[16:19], v[188:191], v[212:215], v[16:19]
	v_mfma_f32_16x16x32_bf16 v[8:11], v[172:175], v[222:225], v[8:11]
	v_mfma_f32_16x16x32_bf16 v[0:3], v[188:191], v[222:225], v[0:3]
	v_mfma_f32_16x16x32_bf16 v[56:59], v[184:187], v[200:203], v[56:59]
	v_mfma_f32_16x16x32_bf16 v[48:51], v[192:195], v[200:203], v[48:51]
	v_mfma_f32_16x16x32_bf16 v[40:43], v[184:187], v[208:211], v[40:43]
	v_mfma_f32_16x16x32_bf16 v[32:35], v[192:195], v[208:211], v[32:35]
	v_mfma_f32_16x16x32_bf16 v[24:27], v[184:187], v[216:219], v[24:27]
	v_mfma_f32_16x16x32_bf16 v[16:19], v[192:195], v[216:219], v[16:19]
	v_mfma_f32_16x16x32_bf16 v[8:11], v[184:187], v[226:229], v[8:11]
	v_mfma_f32_16x16x32_bf16 v[0:3], v[192:195], v[226:229], v[0:3]
	s_setprio 0
	s_barrier
	s_add_i32 s65, s65, 2
	s_add_u32 s6, s6, 0x100
	s_addc_u32 s7, s7, 0
	s_add_u32 s63, s63, 0x100
	s_addc_u32 s64, s64, 0
	s_cmp_gt_u32 s65, 13
	s_cbranch_scc0 .LBB0_191
	s_and_b64 vcc, exec, s[36:37]
	s_cbranch_vccz .LBB0_194
	s_barrier
